# up-projection sample-side skinny GEMM: the four weight-fragment loads issued together with counted waits (de-serialised)
# baseline (speedup 1.0000x reference)
.LBB0_2733:
	v_ashrrev_i32_e32 v7, 31, v6
	v_lshlrev_b64 v[12:13], 11, v[6:7]
	v_lshl_add_u64 v[32:33], v[4:5], 0, v[12:13]
	global_load_dwordx4 v[12:15], v[32:33], off
	global_load_dwordx4 v[34:37], v[32:33], off offset:64
	global_load_dwordx4 v[38:41], v[32:33], off offset:128
	global_load_dwordx4 v[42:45], v[32:33], off offset:192
	ds_read_b128 v[16:19], v1
	ds_read_b128 v[20:23], v1 offset:33024
	s_add_i32 s1, s1, s10
	s_cmpk_lt_i32 s1, 0x100
	s_waitcnt vmcnt(3) lgkmcnt(1)
	v_mfma_f32_16x16x32_bf16 v[16:19], v[16:19], v[12:15], 0
	s_waitcnt lgkmcnt(0)
	v_mfma_f32_16x16x32_bf16 v[12:15], v[20:23], v[12:15], 0
	ds_read_b128 v[24:27], v1 offset:64
	ds_read_b128 v[28:31], v1 offset:33088
	s_waitcnt vmcnt(2) lgkmcnt(1)
	v_mfma_f32_16x16x32_bf16 v[16:19], v[24:27], v[34:37], v[16:19]
	s_waitcnt lgkmcnt(0)
	v_mfma_f32_16x16x32_bf16 v[12:15], v[28:31], v[34:37], v[12:15]
	ds_read_b128 v[24:27], v1 offset:128
	ds_read_b128 v[28:31], v1 offset:33152
	s_waitcnt vmcnt(1) lgkmcnt(1)
	v_mfma_f32_16x16x32_bf16 v[16:19], v[24:27], v[38:41], v[16:19]
	s_waitcnt lgkmcnt(0)
	v_mfma_f32_16x16x32_bf16 v[12:15], v[28:31], v[38:41], v[12:15]
	ds_read_b128 v[24:27], v1 offset:192
	ds_read_b128 v[28:31], v1 offset:33216
	s_waitcnt vmcnt(0) lgkmcnt(1)
	v_mfma_f32_16x16x32_bf16 v[16:19], v[24:27], v[42:45], v[16:19]
	s_waitcnt lgkmcnt(0)
	v_mfma_f32_16x16x32_bf16 v[12:15], v[28:31], v[42:45], v[12:15]
	s_nop 5
	ds_write_b128 v9, v[16:19]
	s_nop 0
	ds_write_b128 v9, v[12:15] offset:1024
	s_waitcnt lgkmcnt(0)
	s_barrier
	ds_read2st64_b32 v[12:13], v10 offset1:8
	ds_read_b32 v11, v2
	s_waitcnt lgkmcnt(1)
	v_add_f32_e32 v7, 0, v12
	v_add_f32_e32 v7, v7, v13
	ds_read2st64_b32 v[12:13], v10 offset0:16 offset1:24
	s_waitcnt lgkmcnt(0)
	v_add_f32_e32 v7, v7, v12
	v_add_f32_e32 v7, v7, v13
	ds_read2st64_b32 v[12:13], v10 offset0:32 offset1:40
	s_waitcnt lgkmcnt(0)
	v_add_f32_e32 v7, v7, v12
	v_add_f32_e32 v7, v7, v13
	ds_read2st64_b32 v[12:13], v10 offset0:48 offset1:56
	s_waitcnt lgkmcnt(0)
	v_add_f32_e32 v7, v7, v12
	v_add_f32_e32 v7, v7, v13
	v_mul_f32_e32 v7, v7, v11
	v_max_f32_e32 v7, 0, v7
	v_add_u32_e32 v12, v8, v6
	v_mul_f32_e32 v7, v7, v7
	v_ashrrev_i32_e32 v13, 31, v12
	v_cvt_pk_bf16_f32 v7, v7, s0
	v_lshl_add_u64 v[12:13], v[12:13], 1, s[2:3]
	v_add_u32_e32 v6, s0, v6
	global_store_short v[12:13], v7, off
	s_barrier
	s_cbranch_scc1 .LBB0_2733
